# v43 plus grid barrier: non-leader workgroups issue their L1 invalidate before polling the XCC generation word instead of after
# baseline (speedup 1.0000x reference)
; __device__ __forceinline__ unsigned xb_ld(unsigned* p)              { return __hip_atomic_load(p, __ATOMIC_RELAXED, __HIP_MEMORY_SCOPE_AGENT); }
; __device__ __forceinline__ unsigned xb_add(unsigned* p, unsigned v) { return __hip_atomic_fetch_add(p, v, __ATOMIC_RELAXED, __HIP_MEMORY_SCOPE_AGENT); }
; #define XB_SPIN(cond, bar) do { unsigned _sp = 0; while (cond) { __builtin_amdgcn_s_sleep(1); \
;     if ((++_sp & 255u) == 0u) { if (xb_ld(&(bar)[XB_TMO])) break; if (_sp > XB_SPIN_CAP) { atomicAdd(&(bar)[XB_TMO], 1u); break; } } } } while (0)
; __device__ __forceinline__ void xcd_barrier(const XcdBarrier& b) {
;     ...
;     if (threadIdx.x == 0) {
;         unsigned* bar = b.bar;
;         __builtin_amdgcn_s_waitcnt(0);
;         unsigned nloc = b.st[0], nx = b.st[1];
;         if (nloc == 0u) { xcd_barrier_complete(bar, b.x, nloc, nx); b.st[0] = nloc; b.st[1] = nx; }
;         const unsigned old = xb_add(&bar[XB_XSUB(b.x)], 1u);
;         const unsigned gen = old / nloc;
;         if (old + 1u == (gen + 1u) * nloc) {
;             __builtin_amdgcn_fence(__ATOMIC_RELEASE, "agent");
;             asm volatile("s_waitcnt vmcnt(0)" ::: "memory");
;             const unsigned og = xb_add(&bar[XB_TOP], 1u);
;             const unsigned tg = og / nx;
;             if (og + 1u == (tg + 1u) * nx) xb_add(&bar[XB_TOPGEN], 1u);
;             else XB_SPIN(xb_ld(&bar[XB_TOPGEN]) == tg, bar);
;             __builtin_amdgcn_fence(__ATOMIC_ACQUIRE, "agent");
;             xb_add(&bar[XB_XGEN(b.x)], 1u);
;             asm volatile("s_waitcnt vmcnt(0)" ::: "memory");
;         } else {
;             XB_SPIN(xb_ld(&bar[XB_XGEN(b.x)]) == gen, bar);
.LBB0_501:
	v_readlane_b32 s4, v254, 7
	s_lshl_b32 s58, s4, 6
	s_lshl_b64 s[4:5], s[58:59], 2
	v_readlane_b32 s6, v252, 12
	v_readlane_b32 s7, v252, 13
	s_add_u32 s4, s6, s4
	s_addc_u32 s5, s7, s5
	v_mov_b32_e32 v0, 0x1000
	global_atomic_add v4, v0, v244, s[4:5] offset:1024 sc0
	v_cvt_f32_u32_e32 v0, v3
	v_sub_u32_e32 v5, 0, v3
	v_rcp_iflag_f32_e32 v0, v0
	s_nop 0
	v_mul_f32_e32 v0, 0x4f7ffffe, v0
	v_cvt_u32_f32_e32 v0, v0
	v_mul_lo_u32 v5, v5, v0
	v_mul_hi_u32 v5, v0, v5
	v_add_u32_e32 v0, v0, v5
	s_waitcnt vmcnt(0)
	v_mul_hi_u32 v0, v4, v0
	v_mul_lo_u32 v5, v0, v3
	v_sub_u32_e32 v5, v4, v5
	v_add_u32_e32 v6, 1, v0
	v_cmp_ge_u32_e32 vcc, v5, v3
	v_add_u32_e32 v4, 1, v4
	s_nop 0
	v_cndmask_b32_e32 v0, v0, v6, vcc
	v_sub_u32_e32 v6, v5, v3
	v_cndmask_b32_e32 v5, v5, v6, vcc
	v_add_u32_e32 v6, 1, v0
	v_cmp_ge_u32_e32 vcc, v5, v3
	s_nop 1
	v_cndmask_b32_e32 v0, v0, v6, vcc
	v_mul_lo_u32 v5, v3, v0
	v_add_u32_e32 v3, v5, v3
	v_cmp_ne_u32_e32 vcc, v4, v3
	s_and_saveexec_b64 s[6:7], vcc
	s_xor_b64 s[6:7], exec, s[6:7]
	s_cbranch_execz .LBB0_515
	s_waitcnt lgkmcnt(0)
	buffer_inv sc1
	global_load_dword v2, v202, s[4:5] offset:1024 sc1
	s_add_u32 s10, s4, 0x2400
	s_addc_u32 s11, s5, 0
	s_waitcnt vmcnt(0)
	v_cmp_eq_u32_e32 vcc, v2, v0
	s_and_saveexec_b64 s[8:9], vcc
	s_cbranch_execz .LBB0_514
	s_mov_b32 s58, 1
	s_mov_b64 s[12:13], 0
	s_branch .LBB0_505

; __device__ __forceinline__ unsigned xb_ld(unsigned* p)              { return __hip_atomic_load(p, __ATOMIC_RELAXED, __HIP_MEMORY_SCOPE_AGENT); }
; #define XB_SPIN(cond, bar) do { unsigned _sp = 0; while (cond) { __builtin_amdgcn_s_sleep(1); \
;     if ((++_sp & 255u) == 0u) { if (xb_ld(&(bar)[XB_TMO])) break; if (_sp > XB_SPIN_CAP) { atomicAdd(&(bar)[XB_TMO], 1u); break; } } } } while (0)
; __device__ __forceinline__ void xcd_barrier(const XcdBarrier& b) {
;     ...
;         } else {
;             XB_SPIN(xb_ld(&bar[XB_XGEN(b.x)]) == gen, bar);
;             __builtin_amdgcn_fence(__ATOMIC_ACQUIRE, "agent");
;             asm volatile("s_waitcnt vmcnt(0)" ::: "memory");
;         }
.LBB0_514:
	s_or_b64 exec, exec, s[8:9]
	s_waitcnt vmcnt(0)
	s_waitcnt vmcnt(0)
